# prep: x f32->bf16 conversion keeps 8 loads in flight per thread (was 1, latency-bound) when grid==512
# baseline (speedup 1.0000x reference)
; DI void convert_job(const float* __restrict__ src, bf16* __restrict__ dst, size_t n) {
;   size_t n4 = n >> 2;
;   for (size_t i = (size_t)blockIdx.x * 256 + threadIdx.x; i < n4; i += (size_t)gridDim.x * 256) {
;     float4 v = ((const float4*)src)[i];
;     uint2 o; o.x = pack2(v.x, v.y); o.y = pack2(v.z, v.w);
;     ((uint2*)dst)[i] = o;
;   }
; }
; DI void prep_phase(const Params& p, unsigned char* smem) {
;     ...
;   convert_job(p.x, (bf16*)(ws + OFF_XB), (size_t)T_TOK * 1024);
.LBB0_6:
	s_or_b64 exec, exec, s[6:7]
	v_readlane_b32 s0, v255, 0
	v_readlane_b32 s1, v255, 1
	s_lshl_b64 s[0:1], s[0:1], 8
	v_mov_b32_e32 v161, 0
	v_writelane_b32 v255, s0, 7
	v_lshlrev_b32_e32 v6, 4, v160
	v_lshlrev_b32_e32 v4, 3, v160
	v_writelane_b32 v255, s1, 8
	v_lshl_add_u64 v[2:3], s[0:1], 0, v[160:161]
	s_mov_b64 s[0:1], 0x400000
	v_cmp_gt_u64_e32 vcc, s[0:1], v[2:3]
	s_and_saveexec_b64 s[6:7], vcc
	s_cbranch_execz .LBB0_9
	s_load_dwordx2 s[0:1], s[2:3], 0x0
	v_readlane_b32 s14, v255, 0
	s_mov_b32 s5, 0
	s_mov_b32 s4, s26
	v_readlane_b32 s15, v255, 1
	s_lshl_b64 s[10:11], s[4:5], 8
	s_lshl_b64 s[12:13], s[14:15], 12
	s_waitcnt lgkmcnt(0)
	s_add_u32 s0, s0, s12
	v_mov_b32_e32 v7, v161
	s_addc_u32 s1, s1, s13
	v_lshl_add_u64 v[8:9], s[0:1], 0, v[6:7]
	s_lshl_b64 s[0:1], s[14:15], 11
	v_mov_b32_e32 v5, v161
	v_lshl_add_u64 v[10:11], s[0:1], 0, v[4:5]
	v_lshl_add_u64 v[10:11], v[18:19], 0, v[10:11]
	s_mov_b64 s[0:1], 0xc000000
	v_lshl_add_u64 v[8:9], v[8:9], 0, 8
	s_lshl_b64 s[12:13], s[4:5], 12
	v_lshl_add_u64 v[10:11], v[10:11], 0, s[0:1]
	s_lshl_b64 s[14:15], s[4:5], 11
	s_mov_b64 s[16:17], 0
	s_mov_b64 s[18:19], 0x3fffff
	v_mov_b64_e32 v[12:13], v[2:3]
	s_cmp_lg_u32 s26, 0x200
	s_cbranch_scc1 .LBB0_8
	s_mov_b32 s98, 4
.Lmy_xcv:
	global_load_dwordx4 v[20:23], v[8:9], off offset:-8
	v_lshl_add_u64 v[8:9], v[8:9], 0, s[12:13]
	global_load_dwordx4 v[24:27], v[8:9], off offset:-8
	v_lshl_add_u64 v[8:9], v[8:9], 0, s[12:13]
	global_load_dwordx4 v[28:31], v[8:9], off offset:-8
	v_lshl_add_u64 v[8:9], v[8:9], 0, s[12:13]
	global_load_dwordx4 v[32:35], v[8:9], off offset:-8
	v_lshl_add_u64 v[8:9], v[8:9], 0, s[12:13]
	global_load_dwordx4 v[36:39], v[8:9], off offset:-8
	v_lshl_add_u64 v[8:9], v[8:9], 0, s[12:13]
	global_load_dwordx4 v[40:43], v[8:9], off offset:-8
	v_lshl_add_u64 v[8:9], v[8:9], 0, s[12:13]
	global_load_dwordx4 v[44:47], v[8:9], off offset:-8
	v_lshl_add_u64 v[8:9], v[8:9], 0, s[12:13]
	global_load_dwordx4 v[48:51], v[8:9], off offset:-8
	v_lshl_add_u64 v[8:9], v[8:9], 0, s[12:13]
	s_waitcnt vmcnt(7)
	v_cvt_pk_bf16_f32 v20, v20, v21
	v_cvt_pk_bf16_f32 v21, v22, v23
	global_store_dwordx2 v[10:11], v[20:21], off
	v_lshl_add_u64 v[10:11], v[10:11], 0, s[14:15]
	s_waitcnt vmcnt(7)
	v_cvt_pk_bf16_f32 v24, v24, v25
	v_cvt_pk_bf16_f32 v25, v26, v27
	global_store_dwordx2 v[10:11], v[24:25], off
	v_lshl_add_u64 v[10:11], v[10:11], 0, s[14:15]
	s_waitcnt vmcnt(7)
	v_cvt_pk_bf16_f32 v28, v28, v29
	v_cvt_pk_bf16_f32 v29, v30, v31
	global_store_dwordx2 v[10:11], v[28:29], off
	v_lshl_add_u64 v[10:11], v[10:11], 0, s[14:15]
	s_waitcnt vmcnt(7)
	v_cvt_pk_bf16_f32 v32, v32, v33
	v_cvt_pk_bf16_f32 v33, v34, v35
	global_store_dwordx2 v[10:11], v[32:33], off
	v_lshl_add_u64 v[10:11], v[10:11], 0, s[14:15]
	s_waitcnt vmcnt(7)
	v_cvt_pk_bf16_f32 v36, v36, v37
	v_cvt_pk_bf16_f32 v37, v38, v39
	global_store_dwordx2 v[10:11], v[36:37], off
	v_lshl_add_u64 v[10:11], v[10:11], 0, s[14:15]
	s_waitcnt vmcnt(7)
	v_cvt_pk_bf16_f32 v40, v40, v41
	v_cvt_pk_bf16_f32 v41, v42, v43
	global_store_dwordx2 v[10:11], v[40:41], off
	v_lshl_add_u64 v[10:11], v[10:11], 0, s[14:15]
	s_waitcnt vmcnt(7)
	v_cvt_pk_bf16_f32 v44, v44, v45
	v_cvt_pk_bf16_f32 v45, v46, v47
	global_store_dwordx2 v[10:11], v[44:45], off
	v_lshl_add_u64 v[10:11], v[10:11], 0, s[14:15]
	s_waitcnt vmcnt(7)
	v_cvt_pk_bf16_f32 v48, v48, v49
	v_cvt_pk_bf16_f32 v49, v50, v51
	global_store_dwordx2 v[10:11], v[48:49], off
	v_lshl_add_u64 v[10:11], v[10:11], 0, s[14:15]
	s_sub_u32 s98, s98, 1
	s_cmp_lg_u32 s98, 0
	s_cbranch_scc1 .Lmy_xcv
	s_branch .LBB0_9
